# P0 copy rebalanced: waves 0-1 of each adaLN workgroup take one quad item after their adaLN item (288 of 1760), the other workgroups the rest
# baseline (speedup 1.0000x reference)
.LBB0_35:
	s_cmpk_lg_i32 s78, 0x100
	s_cbranch_scc1 .Lp0w_orig
	v_lshrrev_b32_e32 v1, 6, v236
	v_and_b32_e32 v2, 63, v236
	v_readfirstlane_b32 s0, v1
	v_and_b32_e32 v3, 31, v2
	v_lshrrev_b32_e32 v4, 5, v2
	s_nop 3
	s_lshl_b32 s2, s0, 14
	v_bfe_u32 v5, v3, 2, 1
	v_xor_b32_e32 v5, v5, v4
	v_lshlrev_b32_e32 v5, 6, v5
	v_lshl_or_b32 v5, v3, 9, v5
	v_add_u32_e32 v5, s2, v5
	v_and_b32_e32 v6, 3, v3
	v_xor_b32_e32 v7, 0, v6
	v_lshl_add_u32 v7, v7, 4, v5
	v_xor_b32_e32 v8, 1, v6
	v_lshl_add_u32 v8, v8, 4, v5
	v_xor_b32_e32 v9, 2, v6
	v_lshl_add_u32 v9, v9, 4, v5
	v_xor_b32_e32 v10, 3, v6
	v_lshl_add_u32 v10, v10, 4, v5
	v_and_b32_e32 v11, 7, v2
	v_xor_b32_e32 v11, v11, v4
	v_lshrrev_b32_e32 v12, 3, v2
	v_lshlrev_b32_e32 v12, 7, v12
	v_add_u32_e32 v12, s2, v12
	v_xor_b32_e32 v13, 0, v11
	v_lshl_add_u32 v13, v13, 4, v12
	v_xor_b32_e32 v14, 2, v11
	v_lshl_add_u32 v14, v14, 4, v12
	v_xor_b32_e32 v15, 4, v11
	v_lshl_add_u32 v15, v15, 4, v12
	v_xor_b32_e32 v16, 6, v11
	v_lshl_add_u32 v16, v16, 4, v12
	v_lshrrev_b32_e32 v17, 3, v2
	v_lshlrev_b32_e32 v17, 11, v17
	v_and_b32_e32 v18, 7, v2
	v_lshl_or_b32 v17, v18, 4, v17
	s_mov_b32 s24, 0
	s_mov_b32 s3, 0
	s_cmpk_lt_i32 s97, 0x90
	s_cbranch_scc0 .Lp0w_nonada
	s_cmpk_ge_u32 s0, 2
	s_cbranch_scc1 .Lp0w_done
	s_lshl_b32 s1, s97, 1
	s_add_i32 s1, s1, s0
	s_addk_i32 s1, 0x5c0
	s_mov_b32 s3, 1
	s_branch .Lp0w_round

.Lp0w_round:
	s_cmpk_ge_u32 s1, 0x6e0
	s_cbranch_scc1 .Lp0w_done
	s_cmpk_lt_i32 s97, 0x90
	s_cbranch_scc1 .Lp0w_take
	s_cmpk_ge_u32 s1, 0x5c0
	s_cbranch_scc1 .Lp0w_done
.Lp0w_take:
	s_movk_i32 s9, 0x80
	s_cmpk_lt_u32 s1, 0x2c0
	s_cbranch_scc0 .Lp0w_win
	s_mul_i32 s4, s1, 0x5d2
	s_lshr_b32 s4, s4, 16
	s_mul_i32 s5, s4, 44
	s_sub_i32 s5, s1, s5
	s_and_b32 s6, s5, 1
	s_mul_i32 s6, s6, 0xb00
	s_lshr_b32 s7, s5, 1
	s_lshl_b32 s7, s7, 7
	s_add_i32 s6, s6, s7
	s_movk_i32 s8, 0x1600
	v_readlane_b32 s18, v246, 7
	v_readlane_b32 s19, v246, 8
	s_add_u32 s12, s74, 0x100000
	s_addc_u32 s13, s75, 0
	s_cmp_eq_u32 s24, 0
	s_cbranch_scc1 .Lp0w_go
	s_mov_b32 s18, s66
	s_mov_b32 s19, s67
	s_add_u32 s12, s74, 0x2500000
	s_addc_u32 s13, s75, 0
	s_branch .Lp0w_go
